# U sweep: cross-row sum of the zeroed diagonal partials on the f32 matrix core (v_mfma_f32_16x16x4_f32 with a ones operand, as the baseline does) + two row rotations, replacing 8 VALU per batch; on top
# baseline (speedup 1.0000x reference)
.Lus_loop:
	s_barrier
	s_waitcnt vmcnt(12) lgkmcnt(10)
	v_mul_f32_e32 v1, v140, v83
	v_add_f32_dpp v184, v185, v184 quad_perm:[1,1,1,1] row_mask:0xf bank_mask:0xf bound_ctrl:1
	v_add_f32_dpp v186, v187, v186 quad_perm:[3,3,3,3] row_mask:0xf bank_mask:0xf bound_ctrl:1
	v_mfma_f32_16x16x32_fp8_fp8 v[200:203], v[18:19], v[118:119], 0
	v_add_f32_dpp v189, v188, v189 quad_perm:[0,0,0,0] row_mask:0xf bank_mask:0xf bound_ctrl:1
	v_add_f32_dpp v190, v191, v190 quad_perm:[3,3,3,3] row_mask:0xf bank_mask:0xf bound_ctrl:1
	v_mfma_f32_16x16x32_fp8_fp8 v[204:207], v[22:23], v[118:119], 0
	v_add_f32_dpp v194, v195, v194 quad_perm:[3,3,3,3] row_mask:0xf bank_mask:0xf bound_ctrl:1
	v_add_f32_dpp v192, v193, v192 quad_perm:[1,1,1,1] row_mask:0xf bank_mask:0xf bound_ctrl:1
	v_mfma_f32_16x16x32_fp8_fp8 v[228:231], v[26:27], v[118:119], 0
	v_add_f32_dpp v199, v198, v199 quad_perm:[2,2,2,2] row_mask:0xf bank_mask:0xf bound_ctrl:1
	v_add_f32_dpp v196, v197, v196 quad_perm:[1,1,1,1] row_mask:0xf bank_mask:0xf bound_ctrl:1
	v_mfma_f32_16x16x32_fp8_fp8 v[232:235], v[30:31], v[118:119], 0
	v_add_f32_dpp v184, v186, v184 quad_perm:[2,2,2,2] row_mask:0xf bank_mask:0xf bound_ctrl:1
	v_add_f32_dpp v189, v190, v189 quad_perm:[2,2,2,2] row_mask:0xf bank_mask:0xf bound_ctrl:1
	v_mfma_f32_16x16x32_fp8_fp8 v[200:203], v[20:21], v[120:121], v[200:203]
	v_add_f32_dpp v194, v192, v194 quad_perm:[0,0,0,0] row_mask:0xf bank_mask:0xf bound_ctrl:1
	v_add_f32_dpp v199, v196, v199 quad_perm:[0,0,0,0] row_mask:0xf bank_mask:0xf bound_ctrl:1
	v_mfma_f32_16x16x32_fp8_fp8 v[204:207], v[24:25], v[120:121], v[204:207]
	v_cndmask_b32_e64 v146, v189, v184, s[2:3]
	v_cndmask_b32_e64 v142, v199, v194, s[2:3]
	v_mfma_f32_16x16x32_fp8_fp8 v[228:231], v[28:29], v[120:121], v[228:231]
	v_cndmask_b32_e64 v86, v142, v146, s[4:5]
	v_mfma_f32_16x16x32_fp8_fp8 v[232:235], v[32:33], v[120:121], v[232:235]
	v_cndmask_b32_e64 v86, 0, v86, s[6:7]
	v_lshl_add_u32 v145, v70, 10, v92
	global_load_dwordx4 v[18:21], v145, s[98:99]
	v_mfma_f32_16x16x4_f32 v[244:247], v209, v86, 0
	v_lshl_add_u32 v147, v71, 10, v92
	global_load_dwordx4 v[22:25], v147, s[98:99]
	v_lshl_add_u32 v145, v72, 10, v92
	global_load_dwordx4 v[26:29], v145, s[98:99]
	v_lshl_add_u32 v147, v73, 10, v92
	global_load_dwordx4 v[30:33], v147, s[98:99]
	ds_read_b32 v83, v89 offset:8704
	ds_read_b128 v[70:73], v91 offset:1536
	s_nop 2
	v_add_f32_dpp v86, v244, v244 row_ror:12 row_mask:0xf bank_mask:0xf bound_ctrl:1
	s_nop 1
	v_add_f32_dpp v86, v86, v86 row_ror:8 row_mask:0xf bank_mask:0xf bound_ctrl:1
	v_mul_f32_e32 v93, v88, v86
	s_mov_b64 exec, s[8:9]
	ds_write_b32 v89, v93 offset:1024
	s_mov_b64 exec, -1
	s_waitcnt vmcnt(12) lgkmcnt(10)
	v_mul_f32_e32 v88, v139, v84
	v_add_f32_dpp v200, v201, v200 quad_perm:[1,1,1,1] row_mask:0xf bank_mask:0xf bound_ctrl:1
	v_add_f32_dpp v202, v203, v202 quad_perm:[3,3,3,3] row_mask:0xf bank_mask:0xf bound_ctrl:1
	v_mfma_f32_16x16x32_fp8_fp8 v[184:187], v[34:35], v[114:115], 0
	v_add_f32_dpp v205, v204, v205 quad_perm:[0,0,0,0] row_mask:0xf bank_mask:0xf bound_ctrl:1
	v_add_f32_dpp v206, v207, v206 quad_perm:[3,3,3,3] row_mask:0xf bank_mask:0xf bound_ctrl:1
	v_mfma_f32_16x16x32_fp8_fp8 v[188:191], v[38:39], v[114:115], 0
	v_add_f32_dpp v230, v231, v230 quad_perm:[3,3,3,3] row_mask:0xf bank_mask:0xf bound_ctrl:1
	v_add_f32_dpp v228, v229, v228 quad_perm:[1,1,1,1] row_mask:0xf bank_mask:0xf bound_ctrl:1
	v_mfma_f32_16x16x32_fp8_fp8 v[192:195], v[42:43], v[114:115], 0
	v_add_f32_dpp v235, v234, v235 quad_perm:[2,2,2,2] row_mask:0xf bank_mask:0xf bound_ctrl:1
	v_add_f32_dpp v232, v233, v232 quad_perm:[1,1,1,1] row_mask:0xf bank_mask:0xf bound_ctrl:1
	v_mfma_f32_16x16x32_fp8_fp8 v[196:199], v[46:47], v[114:115], 0
	v_add_f32_dpp v200, v202, v200 quad_perm:[2,2,2,2] row_mask:0xf bank_mask:0xf bound_ctrl:1
	v_add_f32_dpp v205, v206, v205 quad_perm:[2,2,2,2] row_mask:0xf bank_mask:0xf bound_ctrl:1
	v_mfma_f32_16x16x32_fp8_fp8 v[184:187], v[36:37], v[116:117], v[184:187]
	v_add_f32_dpp v230, v228, v230 quad_perm:[0,0,0,0] row_mask:0xf bank_mask:0xf bound_ctrl:1
	v_add_f32_dpp v235, v232, v235 quad_perm:[0,0,0,0] row_mask:0xf bank_mask:0xf bound_ctrl:1
	v_mfma_f32_16x16x32_fp8_fp8 v[188:191], v[40:41], v[116:117], v[188:191]
	v_cndmask_b32_e64 v146, v205, v200, s[2:3]
	v_cndmask_b32_e64 v142, v235, v230, s[2:3]
	v_mfma_f32_16x16x32_fp8_fp8 v[192:195], v[44:45], v[116:117], v[192:195]
	v_cndmask_b32_e64 v86, v142, v146, s[4:5]
	v_mfma_f32_16x16x32_fp8_fp8 v[196:199], v[48:49], v[116:117], v[196:199]
	v_cndmask_b32_e64 v86, 0, v86, s[6:7]
	v_lshl_add_u32 v145, v74, 10, v92
	global_load_dwordx4 v[34:37], v145, s[98:99]
	v_mfma_f32_16x16x4_f32 v[244:247], v209, v86, 0
	v_lshl_add_u32 v147, v75, 10, v92
	global_load_dwordx4 v[38:41], v147, s[98:99]
	v_lshl_add_u32 v145, v76, 10, v92
	global_load_dwordx4 v[42:45], v145, s[98:99]
	v_lshl_add_u32 v147, v77, 10, v92
	global_load_dwordx4 v[46:49], v147, s[98:99]
	ds_read_b32 v84, v89 offset:10240
	ds_read_b128 v[74:77], v91 offset:3072
	s_nop 2
	v_add_f32_dpp v86, v244, v244 row_ror:12 row_mask:0xf bank_mask:0xf bound_ctrl:1
	s_nop 1
	v_add_f32_dpp v86, v86, v86 row_ror:8 row_mask:0xf bank_mask:0xf bound_ctrl:1
	v_mul_f32_e32 v93, v1, v86
	s_mov_b64 exec, s[8:9]
	ds_write_b32 v89, v93 offset:2560
	s_mov_b64 exec, -1
	s_waitcnt vmcnt(12) lgkmcnt(10)
	v_mul_f32_e32 v1, v138, v85
	v_add_f32_dpp v184, v185, v184 quad_perm:[1,1,1,1] row_mask:0xf bank_mask:0xf bound_ctrl:1
	v_add_f32_dpp v186, v187, v186 quad_perm:[3,3,3,3] row_mask:0xf bank_mask:0xf bound_ctrl:1
	v_mfma_f32_16x16x32_fp8_fp8 v[200:203], v[50:51], v[110:111], 0
	v_add_f32_dpp v189, v188, v189 quad_perm:[0,0,0,0] row_mask:0xf bank_mask:0xf bound_ctrl:1
	v_add_f32_dpp v190, v191, v190 quad_perm:[3,3,3,3] row_mask:0xf bank_mask:0xf bound_ctrl:1
	v_mfma_f32_16x16x32_fp8_fp8 v[204:207], v[54:55], v[110:111], 0
	v_add_f32_dpp v194, v195, v194 quad_perm:[3,3,3,3] row_mask:0xf bank_mask:0xf bound_ctrl:1
	v_add_f32_dpp v192, v193, v192 quad_perm:[1,1,1,1] row_mask:0xf bank_mask:0xf bound_ctrl:1
	v_mfma_f32_16x16x32_fp8_fp8 v[228:231], v[58:59], v[110:111], 0
	v_add_f32_dpp v199, v198, v199 quad_perm:[2,2,2,2] row_mask:0xf bank_mask:0xf bound_ctrl:1
	v_add_f32_dpp v196, v197, v196 quad_perm:[1,1,1,1] row_mask:0xf bank_mask:0xf bound_ctrl:1
	v_mfma_f32_16x16x32_fp8_fp8 v[232:235], v[62:63], v[110:111], 0
	v_add_f32_dpp v184, v186, v184 quad_perm:[2,2,2,2] row_mask:0xf bank_mask:0xf bound_ctrl:1
	v_add_f32_dpp v189, v190, v189 quad_perm:[2,2,2,2] row_mask:0xf bank_mask:0xf bound_ctrl:1
	v_mfma_f32_16x16x32_fp8_fp8 v[200:203], v[52:53], v[112:113], v[200:203]
	v_add_f32_dpp v194, v192, v194 quad_perm:[0,0,0,0] row_mask:0xf bank_mask:0xf bound_ctrl:1
	v_add_f32_dpp v199, v196, v199 quad_perm:[0,0,0,0] row_mask:0xf bank_mask:0xf bound_ctrl:1
	v_mfma_f32_16x16x32_fp8_fp8 v[204:207], v[56:57], v[112:113], v[204:207]
	v_cndmask_b32_e64 v146, v189, v184, s[2:3]
	v_cndmask_b32_e64 v142, v199, v194, s[2:3]
	v_mfma_f32_16x16x32_fp8_fp8 v[228:231], v[60:61], v[112:113], v[228:231]
	v_cndmask_b32_e64 v86, v142, v146, s[4:5]
	v_mfma_f32_16x16x32_fp8_fp8 v[232:235], v[64:65], v[112:113], v[232:235]
	v_cndmask_b32_e64 v86, 0, v86, s[6:7]
	v_lshl_add_u32 v145, v78, 10, v92
	global_load_dwordx4 v[50:53], v145, s[98:99]
	v_mfma_f32_16x16x4_f32 v[244:247], v209, v86, 0
	v_lshl_add_u32 v147, v79, 10, v92
	global_load_dwordx4 v[54:57], v147, s[98:99]
	v_lshl_add_u32 v145, v80, 10, v92
	global_load_dwordx4 v[58:61], v145, s[98:99]
	v_lshl_add_u32 v147, v81, 10, v92
	global_load_dwordx4 v[62:65], v147, s[98:99]
	ds_read_b32 v85, v89 offset:11776
	ds_read_b128 v[78:81], v91 offset:4608
	s_nop 2
	v_add_f32_dpp v86, v244, v244 row_ror:12 row_mask:0xf bank_mask:0xf bound_ctrl:1
	s_nop 1
	v_add_f32_dpp v86, v86, v86 row_ror:8 row_mask:0xf bank_mask:0xf bound_ctrl:1
	v_mul_f32_e32 v93, v88, v86
	s_mov_b64 exec, s[8:9]
	ds_write_b32 v89, v93 offset:4096
	s_mov_b64 exec, -1
	s_waitcnt vmcnt(12) lgkmcnt(10)
	v_mul_f32_e32 v88, v137, v82
	v_add_f32_dpp v200, v201, v200 quad_perm:[1,1,1,1] row_mask:0xf bank_mask:0xf bound_ctrl:1
	v_add_f32_dpp v202, v203, v202 quad_perm:[3,3,3,3] row_mask:0xf bank_mask:0xf bound_ctrl:1
	v_mfma_f32_16x16x32_fp8_fp8 v[184:187], v[2:3], v[106:107], 0
	v_add_f32_dpp v205, v204, v205 quad_perm:[0,0,0,0] row_mask:0xf bank_mask:0xf bound_ctrl:1
	v_add_f32_dpp v206, v207, v206 quad_perm:[3,3,3,3] row_mask:0xf bank_mask:0xf bound_ctrl:1
	v_mfma_f32_16x16x32_fp8_fp8 v[188:191], v[6:7], v[106:107], 0
	v_add_f32_dpp v230, v231, v230 quad_perm:[3,3,3,3] row_mask:0xf bank_mask:0xf bound_ctrl:1
	v_add_f32_dpp v228, v229, v228 quad_perm:[1,1,1,1] row_mask:0xf bank_mask:0xf bound_ctrl:1
	v_mfma_f32_16x16x32_fp8_fp8 v[192:195], v[10:11], v[106:107], 0
	v_add_f32_dpp v235, v234, v235 quad_perm:[2,2,2,2] row_mask:0xf bank_mask:0xf bound_ctrl:1
	v_add_f32_dpp v232, v233, v232 quad_perm:[1,1,1,1] row_mask:0xf bank_mask:0xf bound_ctrl:1
	v_mfma_f32_16x16x32_fp8_fp8 v[196:199], v[14:15], v[106:107], 0
	v_add_f32_dpp v200, v202, v200 quad_perm:[2,2,2,2] row_mask:0xf bank_mask:0xf bound_ctrl:1
	v_add_f32_dpp v205, v206, v205 quad_perm:[2,2,2,2] row_mask:0xf bank_mask:0xf bound_ctrl:1
	v_mfma_f32_16x16x32_fp8_fp8 v[184:187], v[4:5], v[108:109], v[184:187]
	v_add_f32_dpp v230, v228, v230 quad_perm:[0,0,0,0] row_mask:0xf bank_mask:0xf bound_ctrl:1
	v_add_f32_dpp v235, v232, v235 quad_perm:[0,0,0,0] row_mask:0xf bank_mask:0xf bound_ctrl:1
	v_mfma_f32_16x16x32_fp8_fp8 v[188:191], v[8:9], v[108:109], v[188:191]
	v_cndmask_b32_e64 v146, v205, v200, s[2:3]
	v_cndmask_b32_e64 v142, v235, v230, s[2:3]
	v_mfma_f32_16x16x32_fp8_fp8 v[192:195], v[12:13], v[108:109], v[192:195]
	v_cndmask_b32_e64 v86, v142, v146, s[4:5]
	v_mfma_f32_16x16x32_fp8_fp8 v[196:199], v[16:17], v[108:109], v[196:199]
	v_cndmask_b32_e64 v86, 0, v86, s[6:7]
	v_lshl_add_u32 v145, v66, 10, v92
	global_load_dwordx4 v[2:5], v145, s[98:99]
	v_mfma_f32_16x16x4_f32 v[244:247], v209, v86, 0
	v_lshl_add_u32 v147, v67, 10, v92
	global_load_dwordx4 v[6:9], v147, s[98:99]
	v_lshl_add_u32 v145, v68, 10, v92
	global_load_dwordx4 v[10:13], v145, s[98:99]
	v_lshl_add_u32 v147, v69, 10, v92
	global_load_dwordx4 v[14:17], v147, s[98:99]
	ds_read_b32 v82, v90 offset:1024
	ds_read_b128 v[66:69], v91 offset:6144
	s_nop 2
	v_add_f32_dpp v86, v244, v244 row_ror:12 row_mask:0xf bank_mask:0xf bound_ctrl:1
	s_nop 1
	v_add_f32_dpp v86, v86, v86 row_ror:8 row_mask:0xf bank_mask:0xf bound_ctrl:1
	v_mul_f32_e32 v93, v1, v86
	s_mov_b64 exec, s[8:9]
	ds_write_b32 v89, v93 offset:5632
	s_mov_b64 exec, -1
	s_waitcnt vmcnt(12) lgkmcnt(10)
	v_mul_f32_e32 v1, v136, v83
	v_add_f32_dpp v184, v185, v184 quad_perm:[1,1,1,1] row_mask:0xf bank_mask:0xf bound_ctrl:1
	v_add_f32_dpp v186, v187, v186 quad_perm:[3,3,3,3] row_mask:0xf bank_mask:0xf bound_ctrl:1
	v_mfma_f32_16x16x32_fp8_fp8 v[200:203], v[18:19], v[102:103], 0
	v_add_f32_dpp v189, v188, v189 quad_perm:[0,0,0,0] row_mask:0xf bank_mask:0xf bound_ctrl:1
	v_add_f32_dpp v190, v191, v190 quad_perm:[3,3,3,3] row_mask:0xf bank_mask:0xf bound_ctrl:1
	v_mfma_f32_16x16x32_fp8_fp8 v[204:207], v[22:23], v[102:103], 0
	v_add_f32_dpp v194, v195, v194 quad_perm:[3,3,3,3] row_mask:0xf bank_mask:0xf bound_ctrl:1
	v_add_f32_dpp v192, v193, v192 quad_perm:[1,1,1,1] row_mask:0xf bank_mask:0xf bound_ctrl:1
	v_mfma_f32_16x16x32_fp8_fp8 v[228:231], v[26:27], v[102:103], 0
	v_add_f32_dpp v199, v198, v199 quad_perm:[2,2,2,2] row_mask:0xf bank_mask:0xf bound_ctrl:1
	v_add_f32_dpp v196, v197, v196 quad_perm:[1,1,1,1] row_mask:0xf bank_mask:0xf bound_ctrl:1
	v_mfma_f32_16x16x32_fp8_fp8 v[232:235], v[30:31], v[102:103], 0
	v_add_f32_dpp v184, v186, v184 quad_perm:[2,2,2,2] row_mask:0xf bank_mask:0xf bound_ctrl:1
	v_add_f32_dpp v189, v190, v189 quad_perm:[2,2,2,2] row_mask:0xf bank_mask:0xf bound_ctrl:1
	v_mfma_f32_16x16x32_fp8_fp8 v[200:203], v[20:21], v[104:105], v[200:203]
	v_add_f32_dpp v194, v192, v194 quad_perm:[0,0,0,0] row_mask:0xf bank_mask:0xf bound_ctrl:1
	v_add_f32_dpp v199, v196, v199 quad_perm:[0,0,0,0] row_mask:0xf bank_mask:0xf bound_ctrl:1
	v_mfma_f32_16x16x32_fp8_fp8 v[204:207], v[24:25], v[104:105], v[204:207]
	v_cndmask_b32_e64 v146, v189, v184, s[2:3]
	v_cndmask_b32_e64 v142, v199, v194, s[2:3]
	v_mfma_f32_16x16x32_fp8_fp8 v[228:231], v[28:29], v[104:105], v[228:231]
	v_cndmask_b32_e64 v86, v142, v146, s[4:5]
	v_mfma_f32_16x16x32_fp8_fp8 v[232:235], v[32:33], v[104:105], v[232:235]
	v_cndmask_b32_e64 v86, 0, v86, s[6:7]
	v_lshl_add_u32 v145, v70, 10, v92
	global_load_dwordx4 v[18:21], v145, s[98:99]
	v_mfma_f32_16x16x4_f32 v[244:247], v209, v86, 0
	v_lshl_add_u32 v147, v71, 10, v92
	global_load_dwordx4 v[22:25], v147, s[98:99]
	v_lshl_add_u32 v145, v72, 10, v92
	global_load_dwordx4 v[26:29], v145, s[98:99]
	v_lshl_add_u32 v147, v73, 10, v92
	global_load_dwordx4 v[30:33], v147, s[98:99]
	ds_read_b32 v83, v90 offset:2560
	ds_read_b128 v[70:73], v91 offset:7680
	s_nop 2
	v_add_f32_dpp v86, v244, v244 row_ror:12 row_mask:0xf bank_mask:0xf bound_ctrl:1
	s_nop 1
	v_add_f32_dpp v86, v86, v86 row_ror:8 row_mask:0xf bank_mask:0xf bound_ctrl:1
	v_mul_f32_e32 v93, v88, v86
	s_mov_b64 exec, s[8:9]
	ds_write_b32 v89, v93 offset:7168
	s_mov_b64 exec, -1
	s_waitcnt vmcnt(12) lgkmcnt(10)
	v_mul_f32_e32 v88, v129, v84
	v_add_f32_dpp v200, v201, v200 quad_perm:[1,1,1,1] row_mask:0xf bank_mask:0xf bound_ctrl:1
	v_add_f32_dpp v202, v203, v202 quad_perm:[3,3,3,3] row_mask:0xf bank_mask:0xf bound_ctrl:1
	v_mfma_f32_16x16x32_fp8_fp8 v[184:187], v[34:35], v[98:99], 0
	v_add_f32_dpp v205, v204, v205 quad_perm:[0,0,0,0] row_mask:0xf bank_mask:0xf bound_ctrl:1
	v_add_f32_dpp v206, v207, v206 quad_perm:[3,3,3,3] row_mask:0xf bank_mask:0xf bound_ctrl:1
	v_mfma_f32_16x16x32_fp8_fp8 v[188:191], v[38:39], v[98:99], 0
	v_add_f32_dpp v230, v231, v230 quad_perm:[3,3,3,3] row_mask:0xf bank_mask:0xf bound_ctrl:1
	v_add_f32_dpp v228, v229, v228 quad_perm:[1,1,1,1] row_mask:0xf bank_mask:0xf bound_ctrl:1
	v_mfma_f32_16x16x32_fp8_fp8 v[192:195], v[42:43], v[98:99], 0
	v_add_f32_dpp v235, v234, v235 quad_perm:[2,2,2,2] row_mask:0xf bank_mask:0xf bound_ctrl:1
	v_add_f32_dpp v232, v233, v232 quad_perm:[1,1,1,1] row_mask:0xf bank_mask:0xf bound_ctrl:1
	v_mfma_f32_16x16x32_fp8_fp8 v[196:199], v[46:47], v[98:99], 0
	v_add_f32_dpp v200, v202, v200 quad_perm:[2,2,2,2] row_mask:0xf bank_mask:0xf bound_ctrl:1
	v_add_f32_dpp v205, v206, v205 quad_perm:[2,2,2,2] row_mask:0xf bank_mask:0xf bound_ctrl:1
	v_mfma_f32_16x16x32_fp8_fp8 v[184:187], v[36:37], v[100:101], v[184:187]
	v_add_f32_dpp v230, v228, v230 quad_perm:[0,0,0,0] row_mask:0xf bank_mask:0xf bound_ctrl:1
	v_add_f32_dpp v235, v232, v235 quad_perm:[0,0,0,0] row_mask:0xf bank_mask:0xf bound_ctrl:1
	v_mfma_f32_16x16x32_fp8_fp8 v[188:191], v[40:41], v[100:101], v[188:191]
	v_cndmask_b32_e64 v146, v205, v200, s[2:3]
	v_cndmask_b32_e64 v142, v235, v230, s[2:3]
	v_mfma_f32_16x16x32_fp8_fp8 v[192:195], v[44:45], v[100:101], v[192:195]
	v_cndmask_b32_e64 v86, v142, v146, s[4:5]
	v_mfma_f32_16x16x32_fp8_fp8 v[196:199], v[48:49], v[100:101], v[196:199]
	v_cndmask_b32_e64 v86, 0, v86, s[6:7]
	v_lshl_add_u32 v145, v74, 10, v92
	global_load_dwordx4 v[34:37], v145, s[98:99]
	v_mfma_f32_16x16x4_f32 v[244:247], v209, v86, 0
	v_lshl_add_u32 v147, v75, 10, v92
	global_load_dwordx4 v[38:41], v147, s[98:99]
	v_lshl_add_u32 v145, v76, 10, v92
	global_load_dwordx4 v[42:45], v145, s[98:99]
	v_lshl_add_u32 v147, v77, 10, v92
	global_load_dwordx4 v[46:49], v147, s[98:99]
	ds_read_b32 v84, v90 offset:4096
	ds_read_b128 v[74:77], v91 offset:9216
	s_nop 2
	v_add_f32_dpp v86, v244, v244 row_ror:12 row_mask:0xf bank_mask:0xf bound_ctrl:1
	s_nop 1
	v_add_f32_dpp v86, v86, v86 row_ror:8 row_mask:0xf bank_mask:0xf bound_ctrl:1
	v_mul_f32_e32 v93, v1, v86
	s_mov_b64 exec, s[8:9]
	ds_write_b32 v89, v93 offset:8704
	s_mov_b64 exec, -1
	s_waitcnt vmcnt(12) lgkmcnt(10)
	v_mul_f32_e32 v1, v128, v85
	v_add_f32_dpp v184, v185, v184 quad_perm:[1,1,1,1] row_mask:0xf bank_mask:0xf bound_ctrl:1
	v_add_f32_dpp v186, v187, v186 quad_perm:[3,3,3,3] row_mask:0xf bank_mask:0xf bound_ctrl:1
	v_mfma_f32_16x16x32_fp8_fp8 v[200:203], v[50:51], v[94:95], 0
	v_add_f32_dpp v189, v188, v189 quad_perm:[0,0,0,0] row_mask:0xf bank_mask:0xf bound_ctrl:1
	v_add_f32_dpp v190, v191, v190 quad_perm:[3,3,3,3] row_mask:0xf bank_mask:0xf bound_ctrl:1
	v_mfma_f32_16x16x32_fp8_fp8 v[204:207], v[54:55], v[94:95], 0
	v_add_f32_dpp v194, v195, v194 quad_perm:[3,3,3,3] row_mask:0xf bank_mask:0xf bound_ctrl:1
	v_add_f32_dpp v192, v193, v192 quad_perm:[1,1,1,1] row_mask:0xf bank_mask:0xf bound_ctrl:1
	v_mfma_f32_16x16x32_fp8_fp8 v[228:231], v[58:59], v[94:95], 0
	v_add_f32_dpp v199, v198, v199 quad_perm:[2,2,2,2] row_mask:0xf bank_mask:0xf bound_ctrl:1
	v_add_f32_dpp v196, v197, v196 quad_perm:[1,1,1,1] row_mask:0xf bank_mask:0xf bound_ctrl:1
	v_mfma_f32_16x16x32_fp8_fp8 v[232:235], v[62:63], v[94:95], 0
	v_add_f32_dpp v184, v186, v184 quad_perm:[2,2,2,2] row_mask:0xf bank_mask:0xf bound_ctrl:1
	v_add_f32_dpp v189, v190, v189 quad_perm:[2,2,2,2] row_mask:0xf bank_mask:0xf bound_ctrl:1
	v_mfma_f32_16x16x32_fp8_fp8 v[200:203], v[52:53], v[96:97], v[200:203]
	v_add_f32_dpp v194, v192, v194 quad_perm:[0,0,0,0] row_mask:0xf bank_mask:0xf bound_ctrl:1
	v_add_f32_dpp v199, v196, v199 quad_perm:[0,0,0,0] row_mask:0xf bank_mask:0xf bound_ctrl:1
	v_mfma_f32_16x16x32_fp8_fp8 v[204:207], v[56:57], v[96:97], v[204:207]
	v_cndmask_b32_e64 v146, v189, v184, s[2:3]
	v_cndmask_b32_e64 v142, v199, v194, s[2:3]
	v_mfma_f32_16x16x32_fp8_fp8 v[228:231], v[60:61], v[96:97], v[228:231]
	v_cndmask_b32_e64 v86, v142, v146, s[4:5]
	v_mfma_f32_16x16x32_fp8_fp8 v[232:235], v[64:65], v[96:97], v[232:235]
	v_cndmask_b32_e64 v86, 0, v86, s[6:7]
	v_lshl_add_u32 v145, v78, 10, v92
	global_load_dwordx4 v[50:53], v145, s[98:99]
	v_mfma_f32_16x16x4_f32 v[244:247], v209, v86, 0
	v_lshl_add_u32 v147, v79, 10, v92
	global_load_dwordx4 v[54:57], v147, s[98:99]
	v_lshl_add_u32 v145, v80, 10, v92
	global_load_dwordx4 v[58:61], v145, s[98:99]
	v_lshl_add_u32 v147, v81, 10, v92
	global_load_dwordx4 v[62:65], v147, s[98:99]
	ds_read_b32 v85, v90 offset:5632
	ds_read_b128 v[78:81], v91 offset:10752
	s_nop 2
	v_add_f32_dpp v86, v244, v244 row_ror:12 row_mask:0xf bank_mask:0xf bound_ctrl:1
	s_nop 1
	v_add_f32_dpp v86, v86, v86 row_ror:8 row_mask:0xf bank_mask:0xf bound_ctrl:1
	v_mul_f32_e32 v93, v88, v86
	s_mov_b64 exec, s[8:9]
	ds_write_b32 v89, v93 offset:10240
	s_mov_b64 exec, -1
	s_waitcnt vmcnt(12) lgkmcnt(10)
	s_add_i32 s10, s35, 1
	s_min_u32 s10, s10, 31
	s_sub_i32 s11, s35, 1
	s_max_i32 s11, s11, 0
	s_cmp_lg_u64 s[0:1], 0
	s_cselect_b32 s72, s10, s11
	s_lshl_b32 s36, s72, 4
	s_add_i32 s10, s93, s36
	v_mov_b32_e32 v91, s10
	v_mul_f32_e32 v88, v141, v82
	v_add_f32_dpp v200, v201, v200 quad_perm:[1,1,1,1] row_mask:0xf bank_mask:0xf bound_ctrl:1
	v_add_f32_dpp v202, v203, v202 quad_perm:[3,3,3,3] row_mask:0xf bank_mask:0xf bound_ctrl:1
	v_mfma_f32_16x16x32_fp8_fp8 v[184:187], v[2:3], v[122:123], 0
	v_add_f32_dpp v205, v204, v205 quad_perm:[0,0,0,0] row_mask:0xf bank_mask:0xf bound_ctrl:1
	v_add_f32_dpp v206, v207, v206 quad_perm:[3,3,3,3] row_mask:0xf bank_mask:0xf bound_ctrl:1
	v_mfma_f32_16x16x32_fp8_fp8 v[188:191], v[6:7], v[122:123], 0
	v_add_f32_dpp v230, v231, v230 quad_perm:[3,3,3,3] row_mask:0xf bank_mask:0xf bound_ctrl:1
	v_add_f32_dpp v228, v229, v228 quad_perm:[1,1,1,1] row_mask:0xf bank_mask:0xf bound_ctrl:1
	v_mfma_f32_16x16x32_fp8_fp8 v[192:195], v[10:11], v[122:123], 0
	v_add_f32_dpp v235, v234, v235 quad_perm:[2,2,2,2] row_mask:0xf bank_mask:0xf bound_ctrl:1
	v_add_f32_dpp v232, v233, v232 quad_perm:[1,1,1,1] row_mask:0xf bank_mask:0xf bound_ctrl:1
	v_mfma_f32_16x16x32_fp8_fp8 v[196:199], v[14:15], v[122:123], 0
	v_add_f32_dpp v200, v202, v200 quad_perm:[2,2,2,2] row_mask:0xf bank_mask:0xf bound_ctrl:1
	v_add_f32_dpp v205, v206, v205 quad_perm:[2,2,2,2] row_mask:0xf bank_mask:0xf bound_ctrl:1
	v_mfma_f32_16x16x32_fp8_fp8 v[184:187], v[4:5], v[124:125], v[184:187]
	v_add_f32_dpp v230, v228, v230 quad_perm:[0,0,0,0] row_mask:0xf bank_mask:0xf bound_ctrl:1
	v_add_f32_dpp v235, v232, v235 quad_perm:[0,0,0,0] row_mask:0xf bank_mask:0xf bound_ctrl:1
	v_mfma_f32_16x16x32_fp8_fp8 v[188:191], v[8:9], v[124:125], v[188:191]
	v_cndmask_b32_e64 v146, v205, v200, s[2:3]
	v_cndmask_b32_e64 v142, v235, v230, s[2:3]
	v_mfma_f32_16x16x32_fp8_fp8 v[192:195], v[12:13], v[124:125], v[192:195]
	v_cndmask_b32_e64 v86, v142, v146, s[4:5]
	v_mfma_f32_16x16x32_fp8_fp8 v[196:199], v[16:17], v[124:125], v[196:199]
	v_cndmask_b32_e64 v86, 0, v86, s[6:7]
	v_lshl_add_u32 v145, v66, 10, v92
	global_load_dwordx4 v[2:5], v145, s[98:99]
	v_mfma_f32_16x16x4_f32 v[244:247], v209, v86, 0
	v_lshl_add_u32 v147, v67, 10, v92
	global_load_dwordx4 v[6:9], v147, s[98:99]
	v_lshl_add_u32 v145, v68, 10, v92
	global_load_dwordx4 v[10:13], v145, s[98:99]
	v_lshl_add_u32 v147, v69, 10, v92
	global_load_dwordx4 v[14:17], v147, s[98:99]
	ds_read_b32 v82, v90 offset:7168
	ds_read_b128 v[66:69], v91 offset:0
	s_nop 2
	v_add_f32_dpp v86, v244, v244 row_ror:12 row_mask:0xf bank_mask:0xf bound_ctrl:1
	s_nop 1
	v_add_f32_dpp v86, v86, v86 row_ror:8 row_mask:0xf bank_mask:0xf bound_ctrl:1
	v_mul_f32_e32 v93, v1, v86
	s_mov_b64 exec, s[8:9]
	ds_write_b32 v89, v93 offset:11776
	s_mov_b64 exec, -1
	v_mov_b32_e32 v89, v90
	v_add_u32_e32 v90, s36, v181
	s_mov_b32 s34, s35
	s_mov_b32 s35, s72
	s_add_i32 s95, s95, 1
	s_cmp_eq_u32 s95, 32
	s_cbranch_scc0 .Lus_loop
	s_waitcnt vmcnt(0) lgkmcnt(0)
	s_waitcnt lgkmcnt(0)
	s_waitcnt vmcnt(4)
	ds_read2st64_b32 v[2:3], v178 offset0:2 offset1:3
	ds_read2st64_b32 v[4:5], v178 offset0:4 offset1:5
	s_mov_b32 s0, 0x3e6d3388
	s_waitcnt lgkmcnt(0)
	v_fma_f32 v1, |v4|, s0, 1.0
	v_rcp_f32_e32 v1, v1
	v_cmp_gt_f32_e32 vcc, 0, v4
	v_fmamk_f32 v6, v1, 0x3f07dc22, v210
	v_fmaak_f32 v6, v1, v6, 0x3f35f0e3
	v_fmaak_f32 v6, v1, v6, 0xbe11a98e
	v_fmaak_f32 v6, v1, v6, 0x3e027906
	v_mul_f32_e32 v1, v1, v6
	v_mul_f32_e32 v6, v4, v4
	v_mul_f32_e32 v6, 0xbf38aa3b, v6
	v_exp_f32_e32 v6, v6
	s_nop 0
	v_mul_f32_e32 v1, v6, v1
	v_mul_f32_e32 v6, v4, v1
	v_fma_f32 v1, -v4, v1, v4
	v_cndmask_b32_e32 v1, v1, v6, vcc
	v_mul_f32_e32 v1, v2, v1
	v_fma_f32 v2, |v5|, s0, 1.0
	v_rcp_f32_e32 v2, v2
	v_cmp_gt_f32_e32 vcc, 0, v5
	v_fmamk_f32 v4, v2, 0x3f07dc22, v210
	v_fmaak_f32 v4, v2, v4, 0x3f35f0e3
	v_fmaak_f32 v4, v2, v4, 0xbe11a98e
	v_fmaak_f32 v4, v2, v4, 0x3e027906
	v_mul_f32_e32 v2, v2, v4
	v_mul_f32_e32 v4, v5, v5
	v_mul_f32_e32 v4, 0xbf38aa3b, v4
	v_exp_f32_e32 v4, v4
	s_nop 0
	v_mul_f32_e32 v2, v4, v2
	v_mul_f32_e32 v4, v5, v2
	v_fma_f32 v2, -v5, v2, v5
	v_cndmask_b32_e32 v2, v2, v4, vcc
	v_mul_f32_e32 v2, v3, v2
	v_max_f32_e64 v3, |v1|, |v2|
	s_nop 1
	v_mov_b32_dpp v4, v3 quad_perm:[1,0,3,2] row_mask:0xf bank_mask:0xf bound_ctrl:1
	v_max_f32_e32 v4, v4, v4
	v_max_f32_e32 v3, v3, v4
	s_nop 1
	v_mov_b32_dpp v4, v3 quad_perm:[2,3,0,1] row_mask:0xf bank_mask:0xf bound_ctrl:1
	v_max_f32_e32 v4, v4, v4
	v_max_f32_e32 v3, v3, v4
	s_nop 1
	v_mov_b32_dpp v4, v3 row_half_mirror row_mask:0xf bank_mask:0xf bound_ctrl:1
	v_max_f32_e32 v4, v4, v4
	v_max_f32_e32 v3, v3, v4
	s_nop 1
	v_mov_b32_dpp v4, v3 row_mirror row_mask:0xf bank_mask:0xf bound_ctrl:1
	v_max_f32_e32 v4, v4, v4
	v_max_f32_e32 v3, v3, v4
	s_nop 0
	v_readlane_b32 s0, v3, 0
	v_readlane_b32 s1, v3, 16
	v_readlane_b32 s10, v3, 32
	v_readlane_b32 s11, v3, 48
	v_max_f32_e64 v3, s1, s1
	v_max_f32_e64 v4, s0, s0
	v_max_f32_e32 v3, v4, v3
	v_max_f32_e64 v4, s11, s11
	v_max_f32_e64 v5, s10, s10
	v_max_f32_e32 v4, v5, v4
	s_mov_b32 s0, 0xda24260
	v_max3_f32 v3, v3, v4, s0
	s_mov_b64 s[0:1], exec
	v_readlane_b32 s10, v254, 21
	v_readlane_b32 s11, v254, 22
	s_and_b64 s[10:11], s[0:1], s[10:11]
	s_mov_b64 exec, s[10:11]
	v_mul_f32_e32 v4, 0x3b888889, v3
	v_mov_b32_e32 v5, s93
	ds_write_b32 v5, v4 offset:14336
	s_or_b64 exec, exec, s[0:1]
	s_mov_b32 s10, 0x43700000
	v_div_scale_f32 v4, s[0:1], v3, v3, s10
	v_rcp_f32_e32 v5, v4
	s_mov_b32 s0, 0x7020c0c
	v_fma_f32 v6, -v4, v5, 1.0
	v_fmac_f32_e32 v5, v6, v5
	v_div_scale_f32 v6, vcc, s10, v3, s10
	v_mul_f32_e32 v7, v6, v5
	v_fma_f32 v8, -v4, v7, v6
	v_fmac_f32_e32 v7, v8, v5
	v_fma_f32 v4, -v4, v7, v6
	v_div_fmas_f32 v4, v4, v5, v7
	v_div_fixup_f32 v3, v4, v3, s10
	v_mul_f32_e32 v4, v3, v1
	v_mul_f32_e32 v5, v3, v2
	v_mov_b32_e32 v6, v155
	v_cvt_pk_fp8_f32 v6, v4, v5
	v_cvt_pk_f32_fp8_e32 v[4:5], v6
	v_fma_f32 v1, v3, v1, -v4
	v_fma_f32 v2, v3, v2, -v5
	v_mov_b32_e32 v4, v155
	v_cvt_pk_fp8_f32 v4, v1, v2
	ds_read2st64_b32 v[2:3], v178 offset1:1
	v_lshlrev_b32_e32 v1, 16, v6
	v_and_b32_e32 v1, 0xff0000, v1
	v_lshlrev_b32_e32 v5, 24, v4
	v_lshlrev_b32_e32 v4, 16, v4
	s_waitcnt lgkmcnt(0)
	v_or3_b32 v1, v2, v1, v5
	v_lshlrev_b32_e32 v2, 8, v6
	v_perm_b32 v2, v4, v2, s0
	v_or_b32_e32 v2, v2, v3
	ds_write2st64_b32 v178, v1, v2 offset0:2 offset1:3
	ds_read2st64_b32 v[2:3], v178 offset0:8 offset1:9
	ds_read2st64_b32 v[4:5], v178 offset0:10 offset1:11
	s_mov_b32 s0, 0x3e6d3388
	s_waitcnt lgkmcnt(0)
	v_fma_f32 v1, |v4|, s0, 1.0
	v_rcp_f32_e32 v1, v1
	v_cmp_gt_f32_e32 vcc, 0, v4
	v_fmamk_f32 v6, v1, 0x3f07dc22, v210
	v_fmaak_f32 v6, v1, v6, 0x3f35f0e3
	v_fmaak_f32 v6, v1, v6, 0xbe11a98e
	v_fmaak_f32 v6, v1, v6, 0x3e027906
	v_mul_f32_e32 v1, v1, v6
	v_mul_f32_e32 v6, v4, v4
	v_mul_f32_e32 v6, 0xbf38aa3b, v6
	v_exp_f32_e32 v6, v6
	s_nop 0
	v_mul_f32_e32 v1, v6, v1
	v_mul_f32_e32 v6, v4, v1
	v_fma_f32 v1, -v4, v1, v4
	v_cndmask_b32_e32 v1, v1, v6, vcc
	v_mul_f32_e32 v1, v2, v1
	v_fma_f32 v2, |v5|, s0, 1.0
	v_rcp_f32_e32 v2, v2
	v_cmp_gt_f32_e32 vcc, 0, v5
	v_fmamk_f32 v4, v2, 0x3f07dc22, v210
	v_fmaak_f32 v4, v2, v4, 0x3f35f0e3
	v_fmaak_f32 v4, v2, v4, 0xbe11a98e
	v_fmaak_f32 v4, v2, v4, 0x3e027906
	v_mul_f32_e32 v2, v2, v4
	v_mul_f32_e32 v4, v5, v5
	v_mul_f32_e32 v4, 0xbf38aa3b, v4
	v_exp_f32_e32 v4, v4
	s_nop 0
	v_mul_f32_e32 v2, v4, v2
	v_mul_f32_e32 v4, v5, v2
	v_fma_f32 v2, -v5, v2, v5
	v_cndmask_b32_e32 v2, v2, v4, vcc
	v_mul_f32_e32 v2, v3, v2
	v_max_f32_e64 v3, |v1|, |v2|
	s_nop 1
	v_mov_b32_dpp v4, v3 quad_perm:[1,0,3,2] row_mask:0xf bank_mask:0xf bound_ctrl:1
	v_max_f32_e32 v4, v4, v4
	v_max_f32_e32 v3, v3, v4
	s_nop 1
	v_mov_b32_dpp v4, v3 quad_perm:[2,3,0,1] row_mask:0xf bank_mask:0xf bound_ctrl:1
	v_max_f32_e32 v4, v4, v4
	v_max_f32_e32 v3, v3, v4
	s_nop 1
	v_mov_b32_dpp v4, v3 row_half_mirror row_mask:0xf bank_mask:0xf bound_ctrl:1
	v_max_f32_e32 v4, v4, v4
	v_max_f32_e32 v3, v3, v4
	s_nop 1
	v_mov_b32_dpp v4, v3 row_mirror row_mask:0xf bank_mask:0xf bound_ctrl:1
	v_max_f32_e32 v4, v4, v4
	v_max_f32_e32 v3, v3, v4
	s_nop 0
	v_readlane_b32 s0, v3, 0
	v_readlane_b32 s1, v3, 16
	v_readlane_b32 s10, v3, 32
	v_readlane_b32 s11, v3, 48
	v_max_f32_e64 v3, s1, s1
	v_max_f32_e64 v4, s0, s0
	v_max_f32_e32 v3, v4, v3
	v_max_f32_e64 v4, s11, s11
	v_max_f32_e64 v5, s10, s10
	v_max_f32_e32 v4, v5, v4
	s_mov_b32 s0, 0xda24260
	v_max3_f32 v3, v3, v4, s0
	s_mov_b64 s[0:1], exec
	v_readlane_b32 s10, v254, 21
	v_readlane_b32 s11, v254, 22
	s_and_b64 s[10:11], s[0:1], s[10:11]
	s_mov_b64 exec, s[10:11]
	v_mul_f32_e32 v4, 0x3b888889, v3
	v_mov_b32_e32 v5, s93
	ds_write_b32 v5, v4 offset:14340
	s_or_b64 exec, exec, s[0:1]
	s_mov_b32 s10, 0x43700000
	v_div_scale_f32 v4, s[0:1], v3, v3, s10
	v_rcp_f32_e32 v5, v4
	s_mov_b32 s0, 0x7020c0c
	v_fma_f32 v6, -v4, v5, 1.0
	v_fmac_f32_e32 v5, v6, v5
	v_div_scale_f32 v6, vcc, s10, v3, s10
	v_mul_f32_e32 v7, v6, v5
	v_fma_f32 v8, -v4, v7, v6
	v_fmac_f32_e32 v7, v8, v5
	v_fma_f32 v4, -v4, v7, v6
	v_div_fmas_f32 v4, v4, v5, v7
	v_div_fixup_f32 v3, v4, v3, s10
	v_mul_f32_e32 v4, v3, v1
	v_mul_f32_e32 v5, v3, v2
	v_mov_b32_e32 v6, v155
	v_cvt_pk_fp8_f32 v6, v4, v5
	v_cvt_pk_f32_fp8_e32 v[4:5], v6
	v_fma_f32 v1, v3, v1, -v4
	v_fma_f32 v2, v3, v2, -v5
	v_mov_b32_e32 v4, v155
	v_cvt_pk_fp8_f32 v4, v1, v2
	ds_read2st64_b32 v[2:3], v178 offset0:6 offset1:7
	v_lshlrev_b32_e32 v1, 16, v6
	v_and_b32_e32 v1, 0xff0000, v1
	v_lshlrev_b32_e32 v5, 24, v4
	v_lshlrev_b32_e32 v4, 16, v4
	s_waitcnt lgkmcnt(0)
	v_or3_b32 v1, v2, v1, v5
	v_lshlrev_b32_e32 v2, 8, v6
	v_perm_b32 v2, v4, v2, s0
	v_or_b32_e32 v2, v2, v3
	ds_write2st64_b32 v178, v1, v2 offset0:8 offset1:9
	ds_read2st64_b32 v[2:3], v178 offset0:14 offset1:15
	ds_read2st64_b32 v[4:5], v178 offset0:16 offset1:17
	s_mov_b32 s0, 0x3e6d3388
	s_waitcnt lgkmcnt(0)
	v_fma_f32 v1, |v4|, s0, 1.0
	v_rcp_f32_e32 v1, v1
	v_cmp_gt_f32_e32 vcc, 0, v4
	v_fmamk_f32 v6, v1, 0x3f07dc22, v210
	v_fmaak_f32 v6, v1, v6, 0x3f35f0e3
	v_fmaak_f32 v6, v1, v6, 0xbe11a98e
	v_fmaak_f32 v6, v1, v6, 0x3e027906
	v_mul_f32_e32 v1, v1, v6
	v_mul_f32_e32 v6, v4, v4
	v_mul_f32_e32 v6, 0xbf38aa3b, v6
	v_exp_f32_e32 v6, v6
	s_nop 0
	v_mul_f32_e32 v1, v6, v1
	v_mul_f32_e32 v6, v4, v1
	v_fma_f32 v1, -v4, v1, v4
	v_cndmask_b32_e32 v1, v1, v6, vcc
	v_mul_f32_e32 v1, v2, v1
	v_fma_f32 v2, |v5|, s0, 1.0
	v_rcp_f32_e32 v2, v2
	v_cmp_gt_f32_e32 vcc, 0, v5
	v_fmamk_f32 v4, v2, 0x3f07dc22, v210
	v_fmaak_f32 v4, v2, v4, 0x3f35f0e3
	v_fmaak_f32 v4, v2, v4, 0xbe11a98e
	v_fmaak_f32 v4, v2, v4, 0x3e027906
	v_mul_f32_e32 v2, v2, v4
	v_mul_f32_e32 v4, v5, v5
	v_mul_f32_e32 v4, 0xbf38aa3b, v4
	v_exp_f32_e32 v4, v4
	s_nop 0
	v_mul_f32_e32 v2, v4, v2
	v_mul_f32_e32 v4, v5, v2
	v_fma_f32 v2, -v5, v2, v5
	v_cndmask_b32_e32 v2, v2, v4, vcc
	v_mul_f32_e32 v2, v3, v2
	v_max_f32_e64 v3, |v1|, |v2|
	s_nop 1
	v_mov_b32_dpp v4, v3 quad_perm:[1,0,3,2] row_mask:0xf bank_mask:0xf bound_ctrl:1
	v_max_f32_e32 v4, v4, v4
	v_max_f32_e32 v3, v3, v4
	s_nop 1
	v_mov_b32_dpp v4, v3 quad_perm:[2,3,0,1] row_mask:0xf bank_mask:0xf bound_ctrl:1
	v_max_f32_e32 v4, v4, v4
	v_max_f32_e32 v3, v3, v4
	s_nop 1
	v_mov_b32_dpp v4, v3 row_half_mirror row_mask:0xf bank_mask:0xf bound_ctrl:1
	v_max_f32_e32 v4, v4, v4
	v_max_f32_e32 v3, v3, v4
	s_nop 1
	v_mov_b32_dpp v4, v3 row_mirror row_mask:0xf bank_mask:0xf bound_ctrl:1
	v_max_f32_e32 v4, v4, v4
	v_max_f32_e32 v3, v3, v4
	s_nop 0
	v_readlane_b32 s0, v3, 0
	v_readlane_b32 s1, v3, 16
	v_readlane_b32 s10, v3, 32
	v_readlane_b32 s11, v3, 48
	v_max_f32_e64 v3, s1, s1
	v_max_f32_e64 v4, s0, s0
	v_max_f32_e32 v3, v4, v3
	v_max_f32_e64 v4, s11, s11
	v_max_f32_e64 v5, s10, s10
	v_max_f32_e32 v4, v5, v4
	s_mov_b32 s0, 0xda24260
	v_max3_f32 v3, v3, v4, s0
	s_mov_b64 s[0:1], exec
	v_readlane_b32 s10, v254, 21
	v_readlane_b32 s11, v254, 22
	s_and_b64 s[10:11], s[0:1], s[10:11]
	s_mov_b64 exec, s[10:11]
	v_mul_f32_e32 v4, 0x3b888889, v3
	v_mov_b32_e32 v5, s93
	ds_write_b32 v5, v4 offset:14344
	s_or_b64 exec, exec, s[0:1]
	s_mov_b32 s10, 0x43700000
	v_div_scale_f32 v4, s[0:1], v3, v3, s10
	v_rcp_f32_e32 v5, v4
	s_mov_b32 s0, 0x7020c0c
	v_fma_f32 v6, -v4, v5, 1.0
	v_fmac_f32_e32 v5, v6, v5
	v_div_scale_f32 v6, vcc, s10, v3, s10
	v_mul_f32_e32 v7, v6, v5
	v_fma_f32 v8, -v4, v7, v6
	v_fmac_f32_e32 v7, v8, v5
	v_fma_f32 v4, -v4, v7, v6
	v_div_fmas_f32 v4, v4, v5, v7
	v_div_fixup_f32 v3, v4, v3, s10
	v_mul_f32_e32 v4, v3, v1
	v_mul_f32_e32 v5, v3, v2
	v_mov_b32_e32 v6, v155
	v_cvt_pk_fp8_f32 v6, v4, v5
	v_cvt_pk_f32_fp8_e32 v[4:5], v6
	v_fma_f32 v1, v3, v1, -v4
	v_fma_f32 v2, v3, v2, -v5
	v_mov_b32_e32 v4, v155
	v_cvt_pk_fp8_f32 v4, v1, v2
	ds_read2st64_b32 v[2:3], v178 offset0:12 offset1:13
	v_lshlrev_b32_e32 v1, 16, v6
	v_and_b32_e32 v1, 0xff0000, v1
	v_lshlrev_b32_e32 v5, 24, v4
	v_lshlrev_b32_e32 v4, 16, v4
	s_waitcnt lgkmcnt(0)
	v_or3_b32 v1, v2, v1, v5
	v_lshlrev_b32_e32 v2, 8, v6
	v_perm_b32 v2, v4, v2, s0
	v_or_b32_e32 v2, v2, v3
	ds_write2st64_b32 v178, v1, v2 offset0:14 offset1:15
	ds_read2st64_b32 v[2:3], v178 offset0:20 offset1:21
	ds_read2st64_b32 v[4:5], v178 offset0:22 offset1:23
	s_mov_b32 s0, 0x3e6d3388
	s_waitcnt lgkmcnt(0)
	v_fma_f32 v1, |v4|, s0, 1.0
	v_rcp_f32_e32 v1, v1
	v_cmp_gt_f32_e32 vcc, 0, v4
	v_fmamk_f32 v6, v1, 0x3f07dc22, v210
	v_fmaak_f32 v6, v1, v6, 0x3f35f0e3
	v_fmaak_f32 v6, v1, v6, 0xbe11a98e
	v_fmaak_f32 v6, v1, v6, 0x3e027906
	v_mul_f32_e32 v1, v1, v6
	v_mul_f32_e32 v6, v4, v4
	v_mul_f32_e32 v6, 0xbf38aa3b, v6
	v_exp_f32_e32 v6, v6
	s_nop 0
	v_mul_f32_e32 v1, v6, v1
	v_mul_f32_e32 v6, v4, v1
	v_fma_f32 v1, -v4, v1, v4
	v_cndmask_b32_e32 v1, v1, v6, vcc
	v_mul_f32_e32 v1, v2, v1
	v_fma_f32 v2, |v5|, s0, 1.0
	v_rcp_f32_e32 v2, v2
	v_cmp_gt_f32_e32 vcc, 0, v5
	v_fmamk_f32 v4, v2, 0x3f07dc22, v210
	v_fmaak_f32 v4, v2, v4, 0x3f35f0e3
	v_fmaak_f32 v4, v2, v4, 0xbe11a98e
	v_fmaak_f32 v4, v2, v4, 0x3e027906
	v_mul_f32_e32 v2, v2, v4
	v_mul_f32_e32 v4, v5, v5
	v_mul_f32_e32 v4, 0xbf38aa3b, v4
	v_exp_f32_e32 v4, v4
	s_nop 0
	v_mul_f32_e32 v2, v4, v2
	v_mul_f32_e32 v4, v5, v2
	v_fma_f32 v2, -v5, v2, v5
	v_cndmask_b32_e32 v2, v2, v4, vcc
	v_mul_f32_e32 v2, v3, v2
	v_max_f32_e64 v3, |v1|, |v2|
	s_nop 1
	v_mov_b32_dpp v4, v3 quad_perm:[1,0,3,2] row_mask:0xf bank_mask:0xf bound_ctrl:1
	v_max_f32_e32 v4, v4, v4
	v_max_f32_e32 v3, v3, v4
	s_nop 1
	v_mov_b32_dpp v4, v3 quad_perm:[2,3,0,1] row_mask:0xf bank_mask:0xf bound_ctrl:1
	v_max_f32_e32 v4, v4, v4
	v_max_f32_e32 v3, v3, v4
	s_nop 1
	v_mov_b32_dpp v4, v3 row_half_mirror row_mask:0xf bank_mask:0xf bound_ctrl:1
	v_max_f32_e32 v4, v4, v4
	v_max_f32_e32 v3, v3, v4
	s_nop 1
	v_mov_b32_dpp v4, v3 row_mirror row_mask:0xf bank_mask:0xf bound_ctrl:1
	v_max_f32_e32 v4, v4, v4
	v_max_f32_e32 v3, v3, v4
	s_nop 0
	v_readlane_b32 s0, v3, 0
	v_readlane_b32 s1, v3, 16
	v_readlane_b32 s10, v3, 32
	v_readlane_b32 s11, v3, 48
	v_max_f32_e64 v3, s1, s1
	v_max_f32_e64 v4, s0, s0
	v_max_f32_e32 v3, v4, v3
	v_max_f32_e64 v4, s11, s11
	v_max_f32_e64 v5, s10, s10
	v_max_f32_e32 v4, v5, v4
	s_mov_b32 s0, 0xda24260
	v_max3_f32 v3, v3, v4, s0
	s_mov_b64 s[0:1], exec
	v_readlane_b32 s10, v254, 21
	v_readlane_b32 s11, v254, 22
	s_and_b64 s[10:11], s[0:1], s[10:11]
	s_mov_b64 exec, s[10:11]
	v_mul_f32_e32 v4, 0x3b888889, v3
	v_mov_b32_e32 v5, s93
	ds_write_b32 v5, v4 offset:14348
	s_or_b64 exec, exec, s[0:1]
	s_mov_b32 s10, 0x43700000
	v_div_scale_f32 v4, s[0:1], v3, v3, s10
	v_rcp_f32_e32 v5, v4
	s_mov_b32 s0, 0x7020c0c
	v_fma_f32 v6, -v4, v5, 1.0
	v_fmac_f32_e32 v5, v6, v5
	v_div_scale_f32 v6, vcc, s10, v3, s10
	v_mul_f32_e32 v7, v6, v5
	v_fma_f32 v8, -v4, v7, v6
	v_fmac_f32_e32 v7, v8, v5
	v_fma_f32 v4, -v4, v7, v6
	v_div_fmas_f32 v4, v4, v5, v7
	v_div_fixup_f32 v3, v4, v3, s10
	v_mul_f32_e32 v4, v3, v1
	v_mul_f32_e32 v5, v3, v2
	v_mov_b32_e32 v6, v155
	v_cvt_pk_fp8_f32 v6, v4, v5
	v_cvt_pk_f32_fp8_e32 v[4:5], v6
	v_fma_f32 v1, v3, v1, -v4
	v_fma_f32 v2, v3, v2, -v5
	v_mov_b32_e32 v4, v155
	v_cvt_pk_fp8_f32 v4, v1, v2
	ds_read2st64_b32 v[2:3], v178 offset0:18 offset1:19
	v_lshlrev_b32_e32 v1, 16, v6
	v_and_b32_e32 v1, 0xff0000, v1
	v_lshlrev_b32_e32 v5, 24, v4
	v_lshlrev_b32_e32 v4, 16, v4
	s_waitcnt lgkmcnt(0)
	v_or3_b32 v1, v2, v1, v5
	v_lshlrev_b32_e32 v2, 8, v6
	v_perm_b32 v2, v4, v2, s0
	v_or_b32_e32 v2, v2, v3
	ds_write2st64_b32 v178, v1, v2 offset0:20 offset1:21
	ds_read2st64_b32 v[2:3], v178 offset0:26 offset1:27
	ds_read2st64_b32 v[4:5], v178 offset0:28 offset1:29
	s_mov_b32 s0, 0x3e6d3388
	s_waitcnt lgkmcnt(0)
	v_fma_f32 v1, |v4|, s0, 1.0
	v_rcp_f32_e32 v1, v1
	v_cmp_gt_f32_e32 vcc, 0, v4
	v_fmamk_f32 v6, v1, 0x3f07dc22, v210
	v_fmaak_f32 v6, v1, v6, 0x3f35f0e3
	v_fmaak_f32 v6, v1, v6, 0xbe11a98e
	v_fmaak_f32 v6, v1, v6, 0x3e027906
	v_mul_f32_e32 v1, v1, v6
	v_mul_f32_e32 v6, v4, v4
	v_mul_f32_e32 v6, 0xbf38aa3b, v6
	v_exp_f32_e32 v6, v6
	s_nop 0
	v_mul_f32_e32 v1, v6, v1
	v_mul_f32_e32 v6, v4, v1
	v_fma_f32 v1, -v4, v1, v4
	v_cndmask_b32_e32 v1, v1, v6, vcc
	v_mul_f32_e32 v1, v2, v1
	v_fma_f32 v2, |v5|, s0, 1.0
	v_rcp_f32_e32 v2, v2
	v_cmp_gt_f32_e32 vcc, 0, v5
	v_fmamk_f32 v4, v2, 0x3f07dc22, v210
	v_fmaak_f32 v4, v2, v4, 0x3f35f0e3
	v_fmaak_f32 v4, v2, v4, 0xbe11a98e
	v_fmaak_f32 v4, v2, v4, 0x3e027906
	v_mul_f32_e32 v2, v2, v4
	v_mul_f32_e32 v4, v5, v5
	v_mul_f32_e32 v4, 0xbf38aa3b, v4
	v_exp_f32_e32 v4, v4
	s_nop 0
	v_mul_f32_e32 v2, v4, v2
	v_mul_f32_e32 v4, v5, v2
	v_fma_f32 v2, -v5, v2, v5
	v_cndmask_b32_e32 v2, v2, v4, vcc
	v_mul_f32_e32 v2, v3, v2
	v_max_f32_e64 v3, |v1|, |v2|
	s_nop 1
	v_mov_b32_dpp v4, v3 quad_perm:[1,0,3,2] row_mask:0xf bank_mask:0xf bound_ctrl:1
	v_max_f32_e32 v4, v4, v4
	v_max_f32_e32 v3, v3, v4
	s_nop 1
	v_mov_b32_dpp v4, v3 quad_perm:[2,3,0,1] row_mask:0xf bank_mask:0xf bound_ctrl:1
	v_max_f32_e32 v4, v4, v4
	v_max_f32_e32 v3, v3, v4
	s_nop 1
	v_mov_b32_dpp v4, v3 row_half_mirror row_mask:0xf bank_mask:0xf bound_ctrl:1
	v_max_f32_e32 v4, v4, v4
	v_max_f32_e32 v3, v3, v4
	s_nop 1
	v_mov_b32_dpp v4, v3 row_mirror row_mask:0xf bank_mask:0xf bound_ctrl:1
	v_max_f32_e32 v4, v4, v4
	v_max_f32_e32 v3, v3, v4
	s_nop 0
	v_readlane_b32 s0, v3, 0
	v_readlane_b32 s1, v3, 16
	v_readlane_b32 s10, v3, 32
	v_readlane_b32 s11, v3, 48
	v_max_f32_e64 v3, s1, s1
	v_max_f32_e64 v4, s0, s0
	v_max_f32_e32 v3, v4, v3
	v_max_f32_e64 v4, s11, s11
	v_max_f32_e64 v5, s10, s10
	v_max_f32_e32 v4, v5, v4
	s_mov_b32 s0, 0xda24260
	v_max3_f32 v3, v3, v4, s0
	s_mov_b64 s[0:1], exec
	v_readlane_b32 s10, v254, 21
	v_readlane_b32 s11, v254, 22
	s_and_b64 s[10:11], s[0:1], s[10:11]
	s_mov_b64 exec, s[10:11]
	v_mul_f32_e32 v4, 0x3b888889, v3
	v_mov_b32_e32 v5, s93
	ds_write_b32 v5, v4 offset:14352
	s_or_b64 exec, exec, s[0:1]
	s_mov_b32 s10, 0x43700000
	v_div_scale_f32 v4, s[0:1], v3, v3, s10
	v_rcp_f32_e32 v5, v4
	s_mov_b32 s0, 0x7020c0c
	v_fma_f32 v6, -v4, v5, 1.0
	v_fmac_f32_e32 v5, v6, v5
	v_div_scale_f32 v6, vcc, s10, v3, s10
	v_mul_f32_e32 v7, v6, v5
	v_fma_f32 v8, -v4, v7, v6
	v_fmac_f32_e32 v7, v8, v5
	v_fma_f32 v4, -v4, v7, v6
	v_div_fmas_f32 v4, v4, v5, v7
	v_div_fixup_f32 v3, v4, v3, s10
	v_mul_f32_e32 v4, v3, v1
	v_mul_f32_e32 v5, v3, v2
	v_mov_b32_e32 v6, v155
	v_cvt_pk_fp8_f32 v6, v4, v5
	v_cvt_pk_f32_fp8_e32 v[4:5], v6
	v_fma_f32 v1, v3, v1, -v4
	v_fma_f32 v2, v3, v2, -v5
	v_mov_b32_e32 v4, v155
	v_cvt_pk_fp8_f32 v4, v1, v2
	ds_read2st64_b32 v[2:3], v178 offset0:24 offset1:25
	v_lshlrev_b32_e32 v1, 16, v6
	v_and_b32_e32 v1, 0xff0000, v1
	v_lshlrev_b32_e32 v5, 24, v4
	v_lshlrev_b32_e32 v4, 16, v4
	s_waitcnt lgkmcnt(0)
	v_or3_b32 v1, v2, v1, v5
	v_lshlrev_b32_e32 v2, 8, v6
	v_perm_b32 v2, v4, v2, s0
	v_or_b32_e32 v2, v2, v3
	ds_write2st64_b32 v178, v1, v2 offset0:26 offset1:27
	ds_read2st64_b32 v[2:3], v178 offset0:32 offset1:33
	ds_read2st64_b32 v[4:5], v178 offset0:34 offset1:35
	s_mov_b32 s0, 0x3e6d3388
	s_waitcnt lgkmcnt(0)
	v_fma_f32 v1, |v4|, s0, 1.0
	v_rcp_f32_e32 v1, v1
	v_cmp_gt_f32_e32 vcc, 0, v4
	v_fmamk_f32 v6, v1, 0x3f07dc22, v210
	v_fmaak_f32 v6, v1, v6, 0x3f35f0e3
	v_fmaak_f32 v6, v1, v6, 0xbe11a98e
	v_fmaak_f32 v6, v1, v6, 0x3e027906
	v_mul_f32_e32 v1, v1, v6
	v_mul_f32_e32 v6, v4, v4
	v_mul_f32_e32 v6, 0xbf38aa3b, v6
	v_exp_f32_e32 v6, v6
	s_nop 0
	v_mul_f32_e32 v1, v6, v1
	v_mul_f32_e32 v6, v4, v1
	v_fma_f32 v1, -v4, v1, v4
	v_cndmask_b32_e32 v1, v1, v6, vcc
	v_mul_f32_e32 v1, v2, v1
	v_fma_f32 v2, |v5|, s0, 1.0
	v_rcp_f32_e32 v2, v2
	v_cmp_gt_f32_e32 vcc, 0, v5
	v_fmamk_f32 v4, v2, 0x3f07dc22, v210
	v_fmaak_f32 v4, v2, v4, 0x3f35f0e3
	v_fmaak_f32 v4, v2, v4, 0xbe11a98e
	v_fmaak_f32 v4, v2, v4, 0x3e027906
	v_mul_f32_e32 v2, v2, v4
	v_mul_f32_e32 v4, v5, v5
	v_mul_f32_e32 v4, 0xbf38aa3b, v4
	v_exp_f32_e32 v4, v4
	s_nop 0
	v_mul_f32_e32 v2, v4, v2
	v_mul_f32_e32 v4, v5, v2
	v_fma_f32 v2, -v5, v2, v5
	v_cndmask_b32_e32 v2, v2, v4, vcc
	v_mul_f32_e32 v2, v3, v2
	v_max_f32_e64 v3, |v1|, |v2|
	s_nop 1
	v_mov_b32_dpp v4, v3 quad_perm:[1,0,3,2] row_mask:0xf bank_mask:0xf bound_ctrl:1
	v_max_f32_e32 v4, v4, v4
	v_max_f32_e32 v3, v3, v4
	s_nop 1
	v_mov_b32_dpp v4, v3 quad_perm:[2,3,0,1] row_mask:0xf bank_mask:0xf bound_ctrl:1
	v_max_f32_e32 v4, v4, v4
	v_max_f32_e32 v3, v3, v4
	s_nop 1
	v_mov_b32_dpp v4, v3 row_half_mirror row_mask:0xf bank_mask:0xf bound_ctrl:1
	v_max_f32_e32 v4, v4, v4
	v_max_f32_e32 v3, v3, v4
	s_nop 1
	v_mov_b32_dpp v4, v3 row_mirror row_mask:0xf bank_mask:0xf bound_ctrl:1
	v_max_f32_e32 v4, v4, v4
	v_max_f32_e32 v3, v3, v4
	s_nop 0
	v_readlane_b32 s0, v3, 0
	v_readlane_b32 s1, v3, 16
	v_readlane_b32 s10, v3, 32
	v_readlane_b32 s11, v3, 48
	v_max_f32_e64 v3, s1, s1
	v_max_f32_e64 v4, s0, s0
	v_max_f32_e32 v3, v4, v3
	v_max_f32_e64 v4, s11, s11
	v_max_f32_e64 v5, s10, s10
	v_max_f32_e32 v4, v5, v4
	s_mov_b32 s0, 0xda24260
	v_max3_f32 v3, v3, v4, s0
	s_mov_b64 s[0:1], exec
	v_readlane_b32 s10, v254, 21
	v_readlane_b32 s11, v254, 22
	s_and_b64 s[10:11], s[0:1], s[10:11]
	s_mov_b64 exec, s[10:11]
	v_mul_f32_e32 v4, 0x3b888889, v3
	v_mov_b32_e32 v5, s93
	ds_write_b32 v5, v4 offset:14356
	s_or_b64 exec, exec, s[0:1]
	s_mov_b32 s10, 0x43700000
	v_div_scale_f32 v4, s[0:1], v3, v3, s10
	v_rcp_f32_e32 v5, v4
	s_mov_b32 s0, 0x7020c0c
	v_fma_f32 v6, -v4, v5, 1.0
	v_fmac_f32_e32 v5, v6, v5
	v_div_scale_f32 v6, vcc, s10, v3, s10
	v_mul_f32_e32 v7, v6, v5
	v_fma_f32 v8, -v4, v7, v6
	v_fmac_f32_e32 v7, v8, v5
	v_fma_f32 v4, -v4, v7, v6
	v_div_fmas_f32 v4, v4, v5, v7
	v_div_fixup_f32 v3, v4, v3, s10
	v_mul_f32_e32 v4, v3, v1
	v_mul_f32_e32 v5, v3, v2
	v_mov_b32_e32 v6, v155
	v_cvt_pk_fp8_f32 v6, v4, v5
	v_cvt_pk_f32_fp8_e32 v[4:5], v6
	v_fma_f32 v1, v3, v1, -v4
	v_fma_f32 v2, v3, v2, -v5
	v_mov_b32_e32 v4, v155
	v_cvt_pk_fp8_f32 v4, v1, v2
	ds_read2st64_b32 v[2:3], v178 offset0:30 offset1:31
	v_lshlrev_b32_e32 v1, 16, v6
	v_and_b32_e32 v1, 0xff0000, v1
	v_lshlrev_b32_e32 v5, 24, v4
	v_lshlrev_b32_e32 v4, 16, v4
	s_waitcnt lgkmcnt(0)
	v_or3_b32 v1, v2, v1, v5
	v_lshlrev_b32_e32 v2, 8, v6
	v_perm_b32 v2, v4, v2, s0
	v_or_b32_e32 v2, v2, v3
	ds_write2st64_b32 v178, v1, v2 offset0:32 offset1:33
	ds_read2st64_b32 v[2:3], v178 offset0:38 offset1:39
	ds_read2st64_b32 v[4:5], v178 offset0:40 offset1:41
	s_mov_b32 s0, 0x3e6d3388
	s_waitcnt lgkmcnt(0)
	v_fma_f32 v1, |v4|, s0, 1.0
	v_rcp_f32_e32 v1, v1
	v_cmp_gt_f32_e32 vcc, 0, v4
	v_fmamk_f32 v6, v1, 0x3f07dc22, v210
	v_fmaak_f32 v6, v1, v6, 0x3f35f0e3
	v_fmaak_f32 v6, v1, v6, 0xbe11a98e
	v_fmaak_f32 v6, v1, v6, 0x3e027906
	v_mul_f32_e32 v1, v1, v6
	v_mul_f32_e32 v6, v4, v4
	v_mul_f32_e32 v6, 0xbf38aa3b, v6
	v_exp_f32_e32 v6, v6
	s_nop 0
	v_mul_f32_e32 v1, v6, v1
	v_mul_f32_e32 v6, v4, v1
	v_fma_f32 v1, -v4, v1, v4
	v_cndmask_b32_e32 v1, v1, v6, vcc
	v_mul_f32_e32 v1, v2, v1
	v_fma_f32 v2, |v5|, s0, 1.0
	v_rcp_f32_e32 v2, v2
	v_cmp_gt_f32_e32 vcc, 0, v5
	v_fmamk_f32 v4, v2, 0x3f07dc22, v210
	v_fmaak_f32 v4, v2, v4, 0x3f35f0e3
	v_fmaak_f32 v4, v2, v4, 0xbe11a98e
	v_fmaak_f32 v4, v2, v4, 0x3e027906
	v_mul_f32_e32 v2, v2, v4
	v_mul_f32_e32 v4, v5, v5
	v_mul_f32_e32 v4, 0xbf38aa3b, v4
	v_exp_f32_e32 v4, v4
	s_nop 0
	v_mul_f32_e32 v2, v4, v2
	v_mul_f32_e32 v4, v5, v2
	v_fma_f32 v2, -v5, v2, v5
	v_cndmask_b32_e32 v2, v2, v4, vcc
	v_mul_f32_e32 v2, v3, v2
	v_max_f32_e64 v3, |v1|, |v2|
	s_nop 1
	v_mov_b32_dpp v4, v3 quad_perm:[1,0,3,2] row_mask:0xf bank_mask:0xf bound_ctrl:1
	v_max_f32_e32 v4, v4, v4
	v_max_f32_e32 v3, v3, v4
	s_nop 1
	v_mov_b32_dpp v4, v3 quad_perm:[2,3,0,1] row_mask:0xf bank_mask:0xf bound_ctrl:1
	v_max_f32_e32 v4, v4, v4
	v_max_f32_e32 v3, v3, v4
	s_nop 1
	v_mov_b32_dpp v4, v3 row_half_mirror row_mask:0xf bank_mask:0xf bound_ctrl:1
	v_max_f32_e32 v4, v4, v4
	v_max_f32_e32 v3, v3, v4
	s_nop 1
	v_mov_b32_dpp v4, v3 row_mirror row_mask:0xf bank_mask:0xf bound_ctrl:1
	v_max_f32_e32 v4, v4, v4
	v_max_f32_e32 v3, v3, v4
	s_nop 0
	v_readlane_b32 s0, v3, 0
	v_readlane_b32 s1, v3, 16
	v_readlane_b32 s10, v3, 32
	v_readlane_b32 s11, v3, 48
	v_max_f32_e64 v3, s1, s1
	v_max_f32_e64 v4, s0, s0
	v_max_f32_e32 v3, v4, v3
	v_max_f32_e64 v4, s11, s11
	v_max_f32_e64 v5, s10, s10
	v_max_f32_e32 v4, v5, v4
	s_mov_b32 s0, 0xda24260
	v_max3_f32 v3, v3, v4, s0
	s_mov_b64 s[0:1], exec
	v_readlane_b32 s10, v254, 21
	v_readlane_b32 s11, v254, 22
	s_and_b64 s[10:11], s[0:1], s[10:11]
	s_mov_b64 exec, s[10:11]
	v_mul_f32_e32 v4, 0x3b888889, v3
	v_mov_b32_e32 v5, s93
	ds_write_b32 v5, v4 offset:14360
	s_or_b64 exec, exec, s[0:1]
	s_mov_b32 s10, 0x43700000
	v_div_scale_f32 v4, s[0:1], v3, v3, s10
	v_rcp_f32_e32 v5, v4
	s_mov_b32 s0, 0x7020c0c
	v_fma_f32 v6, -v4, v5, 1.0
	v_fmac_f32_e32 v5, v6, v5
	v_div_scale_f32 v6, vcc, s10, v3, s10
	v_mul_f32_e32 v7, v6, v5
	v_fma_f32 v8, -v4, v7, v6
	v_fmac_f32_e32 v7, v8, v5
	v_fma_f32 v4, -v4, v7, v6
	v_div_fmas_f32 v4, v4, v5, v7
	v_div_fixup_f32 v3, v4, v3, s10
	v_mul_f32_e32 v4, v3, v1
	v_mul_f32_e32 v5, v3, v2
	v_mov_b32_e32 v6, v155
	v_cvt_pk_fp8_f32 v6, v4, v5
	v_cvt_pk_f32_fp8_e32 v[4:5], v6
	v_fma_f32 v1, v3, v1, -v4
	v_fma_f32 v2, v3, v2, -v5
	v_mov_b32_e32 v4, v155
	v_cvt_pk_fp8_f32 v4, v1, v2
	ds_read2st64_b32 v[2:3], v178 offset0:36 offset1:37
	v_lshlrev_b32_e32 v1, 16, v6
	v_and_b32_e32 v1, 0xff0000, v1
	v_lshlrev_b32_e32 v5, 24, v4
	v_lshlrev_b32_e32 v4, 16, v4
	s_waitcnt lgkmcnt(0)
	v_or3_b32 v1, v2, v1, v5
	v_lshlrev_b32_e32 v2, 8, v6
	v_perm_b32 v2, v4, v2, s0
	v_or_b32_e32 v2, v2, v3
	ds_write2st64_b32 v178, v1, v2 offset0:38 offset1:39
	ds_read2st64_b32 v[2:3], v178 offset0:44 offset1:45
	ds_read2st64_b32 v[4:5], v178 offset0:46 offset1:47
	s_mov_b32 s0, 0x3e6d3388
	s_waitcnt lgkmcnt(0)
	v_fma_f32 v1, |v4|, s0, 1.0
	v_rcp_f32_e32 v1, v1
	v_cmp_gt_f32_e32 vcc, 0, v4
	v_fmamk_f32 v6, v1, 0x3f07dc22, v210
	v_fmaak_f32 v6, v1, v6, 0x3f35f0e3
	v_fmaak_f32 v6, v1, v6, 0xbe11a98e
	v_fmaak_f32 v6, v1, v6, 0x3e027906
	v_mul_f32_e32 v1, v1, v6
	v_mul_f32_e32 v6, v4, v4
	v_mul_f32_e32 v6, 0xbf38aa3b, v6
	v_exp_f32_e32 v6, v6
	s_nop 0
	v_mul_f32_e32 v1, v6, v1
	v_mul_f32_e32 v6, v4, v1
	v_fma_f32 v1, -v4, v1, v4
	v_cndmask_b32_e32 v1, v1, v6, vcc
	v_mul_f32_e32 v1, v2, v1
	v_fma_f32 v2, |v5|, s0, 1.0
	v_rcp_f32_e32 v2, v2
	v_cmp_gt_f32_e32 vcc, 0, v5
	v_fmamk_f32 v4, v2, 0x3f07dc22, v210
	v_fmaak_f32 v4, v2, v4, 0x3f35f0e3
	v_fmaak_f32 v4, v2, v4, 0xbe11a98e
	v_fmaak_f32 v4, v2, v4, 0x3e027906
	v_mul_f32_e32 v2, v2, v4
	v_mul_f32_e32 v4, v5, v5
	v_mul_f32_e32 v4, 0xbf38aa3b, v4
	v_exp_f32_e32 v4, v4
	s_nop 0
	v_mul_f32_e32 v2, v4, v2
	v_mul_f32_e32 v4, v5, v2
	v_fma_f32 v2, -v5, v2, v5
	v_cndmask_b32_e32 v2, v2, v4, vcc
	v_mul_f32_e32 v2, v3, v2
	v_max_f32_e64 v3, |v1|, |v2|
	s_nop 1
	v_mov_b32_dpp v4, v3 quad_perm:[1,0,3,2] row_mask:0xf bank_mask:0xf bound_ctrl:1
	v_max_f32_e32 v4, v4, v4
	v_max_f32_e32 v3, v3, v4
	s_nop 1
	v_mov_b32_dpp v4, v3 quad_perm:[2,3,0,1] row_mask:0xf bank_mask:0xf bound_ctrl:1
	v_max_f32_e32 v4, v4, v4
	v_max_f32_e32 v3, v3, v4
	s_nop 1
	v_mov_b32_dpp v4, v3 row_half_mirror row_mask:0xf bank_mask:0xf bound_ctrl:1
	v_max_f32_e32 v4, v4, v4
	v_max_f32_e32 v3, v3, v4
	s_nop 1
	v_mov_b32_dpp v4, v3 row_mirror row_mask:0xf bank_mask:0xf bound_ctrl:1
	v_max_f32_e32 v4, v4, v4
	v_max_f32_e32 v3, v3, v4
	s_nop 0
	v_readlane_b32 s0, v3, 0
	v_readlane_b32 s1, v3, 16
	v_readlane_b32 s10, v3, 32
	v_readlane_b32 s11, v3, 48
	v_max_f32_e64 v3, s1, s1
	v_max_f32_e64 v4, s0, s0
	v_max_f32_e32 v3, v4, v3
	v_max_f32_e64 v4, s11, s11
	v_max_f32_e64 v5, s10, s10
	v_max_f32_e32 v4, v5, v4
	s_mov_b32 s0, 0xda24260
	v_max3_f32 v3, v3, v4, s0
	s_mov_b64 s[0:1], exec
	v_readlane_b32 s10, v254, 21
	v_readlane_b32 s11, v254, 22
	s_and_b64 s[10:11], s[0:1], s[10:11]
	s_mov_b64 exec, s[10:11]
	v_mul_f32_e32 v4, 0x3b888889, v3
	v_mov_b32_e32 v5, s93
	ds_write_b32 v5, v4 offset:14364
	s_or_b64 exec, exec, s[0:1]
	s_mov_b32 s10, 0x43700000
	v_div_scale_f32 v4, s[0:1], v3, v3, s10
	v_rcp_f32_e32 v5, v4
	s_mov_b32 s0, 0x7020c0c
	v_readlane_b32 s12, v254, 29
	v_fma_f32 v6, -v4, v5, 1.0
	v_fmac_f32_e32 v5, v6, v5
	v_div_scale_f32 v6, vcc, s10, v3, s10
	v_mul_f32_e32 v7, v6, v5
	v_fma_f32 v8, -v4, v7, v6
	v_fmac_f32_e32 v7, v8, v5
	v_fma_f32 v4, -v4, v7, v6
	v_div_fmas_f32 v4, v4, v5, v7
	v_div_fixup_f32 v3, v4, v3, s10
	v_mul_f32_e32 v4, v3, v1
	v_mul_f32_e32 v5, v3, v2
	v_mov_b32_e32 v6, v155
	v_cvt_pk_fp8_f32 v6, v4, v5
	s_mov_b32 s10, 0
	v_cvt_pk_f32_fp8_e32 v[4:5], v6
	v_fma_f32 v1, v3, v1, -v4
	v_fma_f32 v2, v3, v2, -v5
	v_mov_b32_e32 v4, v155
	v_cvt_pk_fp8_f32 v4, v1, v2
	ds_read2st64_b32 v[2:3], v178 offset0:42 offset1:43
	v_lshlrev_b32_e32 v1, 16, v6
	v_and_b32_e32 v1, 0xff0000, v1
	v_lshlrev_b32_e32 v5, 24, v4
	v_lshlrev_b32_e32 v4, 16, v4
	s_waitcnt lgkmcnt(0)
	v_or3_b32 v1, v2, v1, v5
	v_lshlrev_b32_e32 v2, 8, v6
	v_perm_b32 v2, v4, v2, s0
	s_add_i32 s0, s40, 0xffffe000
	s_lshr_b32 s0, s0, 12
	s_add_i32 s0, s0, 1
	s_cmpk_gt_i32 s40, 0x1fff
	s_cselect_b32 s11, s0, 0
	v_readlane_b32 s0, v254, 20
	s_mul_i32 s0, s0, 3
	s_add_i32 s11, s11, s0
	v_or_b32_e32 v2, v2, v3
	s_mul_i32 s1, s11, 0x6000
	ds_write2st64_b32 v178, v1, v2 offset0:44 offset1:45
	s_mul_hi_u32 s0, s11, 0x6000
	s_add_u32 s1, s12, s1
	v_readlane_b32 s12, v254, 30
	s_waitcnt lgkmcnt(0)
	s_addc_u32 s12, s12, s0
	s_add_u32 s0, s1, 0x5000
	s_addc_u32 s1, s12, 0
